# prep section B: the 16-lane sum-of-squares butterflies (ds_bpermute + wait + add) replaced by DPP adds (quad_perm / row_half_mirror / row_mirror), bit-identical
# speedup vs baseline: 1.0092x; 1.0027x over previous
.LBB0_316:
	v_ashrrev_i32_e32 v181, 3, v135
	s_lshr_b32 s0, s23, 7
	v_and_b32_e32 v183, -2, v181
	v_and_b32_e32 v1, 15, v135
	s_lshl_b32 s0, s0, 6
	v_add3_u32 v60, s7, -3, v183
	v_lshlrev_b32_e32 v3, 3, v1
	s_and_b32 s0, s0, 0x180
	v_max_i32_e32 v16, -2, v60
	v_add_u32_e32 v62, s7, v183
	v_or_b32_e32 v61, s0, v3
	v_add_u32_e32 v16, 2, v16
	v_mov_b32_e32 v17, v0
	v_max_i32_e32 v20, 0, v62
	v_mov_b32_e32 v21, v0
	v_lshlrev_b32_e32 v28, 1, v61
	v_mov_b32_e32 v29, v0
	v_max_i32_e32 v12, -1, v60
	v_lshl_add_u64 v[16:17], s[4:5], 0, v[16:17]
	v_lshl_add_u64 v[20:21], s[4:5], 0, v[20:21]
	v_max_i32_e32 v26, -4, v60
	v_lshl_add_u64 v[24:25], s[12:13], 0, v[28:29]
	v_max_i32_e32 v8, 0, v60
	v_mov_b32_e32 v9, v0
	v_add_u32_e32 v12, 1, v12
	v_mov_b32_e32 v13, v0
	v_lshlrev_b64 v[36:37], 12, v[16:17]
	v_lshlrev_b64 v[40:41], 12, v[20:21]
	v_add_u32_e32 v26, 4, v26
	v_mov_b32_e32 v27, v0
	v_lshl_add_u64 v[8:9], s[4:5], 0, v[8:9]
	v_lshl_add_u64 v[12:13], s[4:5], 0, v[12:13]
	v_lshl_add_u64 v[16:17], v[24:25], 0, v[36:37]
	v_lshl_add_u64 v[20:21], v[24:25], 0, v[40:41]
	v_lshl_add_u64 v[26:27], s[4:5], 0, v[26:27]
	s_waitcnt lgkmcnt(0)
	s_barrier
	v_lshlrev_b64 v[30:31], 12, v[8:9]
	v_lshlrev_b64 v[32:33], 12, v[12:13]
	global_load_dwordx4 v[16:19], v[16:17], off
	v_lshlrev_b64 v[44:45], 12, v[26:27]
	global_load_dwordx4 v[20:23], v[20:21], off
	v_lshl_add_u64 v[8:9], v[24:25], 0, v[30:31]
	v_lshl_add_u64 v[12:13], v[24:25], 0, v[32:33]
	v_lshl_add_u64 v[24:25], v[24:25], 0, v[44:45]
	global_load_dwordx4 v[24:27], v[24:25], off
	v_mov_b32_e32 v47, v0
	global_load_dwordx4 v[8:11], v[8:9], off
	v_or_b32_e32 v46, 0x400, v28
	global_load_dwordx4 v[12:15], v[12:13], off
	v_lshl_add_u64 v[54:55], s[12:13], 0, v[40:41]
	v_lshl_add_u64 v[40:41], v[54:55], 0, v[46:47]
	v_lshl_add_u64 v[58:59], s[12:13], 0, v[44:45]
	v_lshl_add_u64 v[48:49], s[12:13], 0, v[30:31]
	v_lshl_add_u64 v[50:51], s[12:13], 0, v[32:33]
	v_lshl_add_u64 v[52:53], s[12:13], 0, v[36:37]
	global_load_dwordx4 v[40:43], v[40:41], off
	v_lshl_add_u64 v[44:45], v[58:59], 0, v[46:47]
	v_lshl_add_u64 v[28:29], v[48:49], 0, v[46:47]
	v_lshl_add_u64 v[32:33], v[50:51], 0, v[46:47]
	v_lshl_add_u64 v[36:37], v[52:53], 0, v[46:47]
	global_load_dwordx4 v[44:47], v[44:45], off
	v_cmp_gt_i32_e64 s[4:5], 0, v62
	v_readlane_b32 s34, v251, 51
	v_lshl_or_b32 v3, s6, 7, v3
	v_readlane_b32 s35, v251, 52
	v_or_b32_e32 v3, 0x400, v3
	v_cmp_gt_i32_e64 s[6:7], -4, v60
	global_load_dwordx4 v[28:31], v[28:29], off
	v_mov_b32_e32 v57, v0
	v_lshlrev_b32_e32 v56, 1, v3
	v_lshl_add_u64 v[48:49], v[48:49], 0, v[56:57]
	v_cmp_gt_i32_e32 vcc, 0, v60
	v_cmp_gt_i32_e64 s[0:1], -1, v60
	v_cmp_gt_i32_e64 s[2:3], -2, v60
	s_movk_i32 s25, 0x4000
	global_load_dwordx4 v[32:35], v[32:33], off
	v_lshl_add_u64 v[50:51], v[50:51], 0, v[56:57]
	global_load_dwordx4 v[36:39], v[36:37], off
	s_nop 0
	global_load_dwordx4 v[104:107], v[48:49], off
	global_load_dwordx4 v[108:111], v[50:51], off
	s_mov_b64 s[28:29], 0x2000
	s_movk_i32 s26, 0x6000
	s_mov_b64 s[30:31], 0x6000
	v_add_u32_e32 v201, 64, v2
	v_lshlrev_b32_e32 v197, 4, v1
	v_lshrrev_b32_e32 v198, 5, v135
	v_bfe_u32 v200, v135, 2, 2
	s_waitcnt vmcnt(11)
	v_cndmask_b32_e64 v161, v16, 0, s[2:3]
	v_cndmask_b32_e64 v129, v17, 0, s[2:3]
	s_waitcnt vmcnt(10)
	v_cndmask_b32_e64 v163, v20, 0, s[4:5]
	v_cndmask_b32_e64 v131, v21, 0, s[4:5]
	v_lshlrev_b32_e32 v20, 2, v61
	v_mov_b32_e32 v21, v0
	v_cndmask_b32_e64 v125, v22, 0, s[4:5]
	v_cndmask_b32_e64 v117, v23, 0, s[4:5]
	v_lshl_add_u64 v[22:23], s[34:35], 0, v[20:21]
	s_waitcnt vmcnt(9)
	v_cndmask_b32_e64 v202, v26, 0, s[6:7]
	v_add_co_u32_e64 v26, s[8:9], s62, v22
	v_cndmask_b32_e64 v203, v27, 0, s[6:7]
	s_nop 0
	v_addc_co_u32_e64 v27, s[8:9], 0, v23, s[8:9]
	s_waitcnt vmcnt(8)
	v_cndmask_b32_e64 v165, v8, 0, vcc
	v_cndmask_b32_e64 v118, v9, 0, vcc
	s_waitcnt vmcnt(7)
	v_cndmask_b32_e64 v133, v12, 0, s[0:1]
	v_cndmask_b32_e64 v127, v13, 0, s[0:1]
	v_lshl_add_u64 v[8:9], v[52:53], 0, v[56:57]
	v_lshl_add_u64 v[12:13], v[54:55], 0, v[56:57]
	v_lshl_add_u64 v[16:17], v[58:59], 0, v[56:57]
	v_add_co_u32_e64 v48, s[8:9], s25, v22
	v_cndmask_b32_e64 v119, v10, 0, vcc
	v_cndmask_b32_e64 v120, v11, 0, vcc
	v_cndmask_b32_e64 v121, v14, 0, s[0:1]
	v_cndmask_b32_e64 v113, v15, 0, s[0:1]
	v_cndmask_b32_e64 v123, v18, 0, s[2:3]
	v_cndmask_b32_e64 v115, v19, 0, s[2:3]
	global_load_dwordx4 v[8:11], v[8:9], off
	v_cndmask_b32_e64 v196, v24, 0, s[6:7]
	global_load_dwordx4 v[12:15], v[12:13], off
	v_cndmask_b32_e64 v199, v25, 0, s[6:7]
	global_load_dwordx4 v[16:19], v[16:17], off
	s_nop 0
	global_load_dwordx4 v[72:75], v20, s[34:35]
	global_load_dwordx4 v[88:91], v20, s[34:35] offset:16
	v_lshl_add_u64 v[24:25], v[22:23], 0, s[28:29]
	v_addc_co_u32_e64 v49, s[8:9], 0, v23, s[8:9]
	global_load_dwordx4 v[76:79], v[26:27], off
	global_load_dwordx4 v[92:95], v[24:25], off offset:16
	v_lshl_add_u64 v[24:25], v[22:23], 0, s[48:49]
	v_add_co_u32_e64 v52, s[8:9], s26, v22
	global_load_dwordx4 v[96:99], v[24:25], off offset:16
	s_nop 0
	v_addc_co_u32_e64 v53, s[8:9], 0, v23, s[8:9]
	v_lshl_add_u64 v[24:25], v[22:23], 0, s[30:31]
	global_load_dwordx4 v[80:83], v[52:53], off
	global_load_dwordx4 v[100:103], v[24:25], off offset:16
	s_mov_b64 s[8:9], 0x2800
	s_waitcnt vmcnt(16)
	v_cndmask_b32_e64 v180, v40, 0, s[4:5]
	v_cndmask_b32_e64 v187, v41, 0, s[4:5]
	v_cndmask_b32_e64 v191, v42, 0, s[4:5]
	v_cndmask_b32_e64 v195, v43, 0, s[4:5]
	global_load_dwordx4 v[40:43], v20, s[34:35] offset:2048
	global_load_dwordx4 v[56:59], v20, s[34:35] offset:2064
	v_lshl_add_u64 v[20:21], v[22:23], 0, s[8:9]
	s_mov_b64 s[8:9], 0x4800
	s_waitcnt vmcnt(17)
	v_cndmask_b32_e64 v172, v44, 0, s[6:7]
	v_cndmask_b32_e64 v174, v45, 0, s[6:7]
	v_cndmask_b32_e64 v175, v46, 0, s[6:7]
	v_cndmask_b32_e64 v176, v47, 0, s[6:7]
	global_load_dwordx4 v[44:47], v[26:27], off offset:2048
	v_lshl_add_u64 v[24:25], v[22:23], 0, s[8:9]
	global_load_dwordx4 v[84:87], v[48:49], off
	s_nop 0
	global_load_dwordx4 v[48:51], v[48:49], off offset:2048
	s_nop 0
	global_load_dwordx4 v[64:67], v[20:21], off offset:16
	global_load_dwordx4 v[68:71], v[24:25], off offset:16
	s_waitcnt vmcnt(18)
	v_cndmask_b32_e64 v148, v105, 0, vcc
	v_cndmask_b32_e64 v168, v104, 0, vcc
	v_lshlrev_b32_e32 v104, 16, v120
	v_and_b32_e32 v105, 0xffff0000, v120
	v_lshlrev_b32_e32 v112, 16, v113
	v_and_b32_e32 v113, 0xffff0000, v113
	v_lshlrev_b32_e32 v114, 16, v115
	v_and_b32_e32 v115, 0xffff0000, v115
	v_lshlrev_b32_e32 v116, 16, v117
	v_and_b32_e32 v117, 0xffff0000, v117
	s_mov_b64 s[8:9], 0x6800
	v_cndmask_b32_e64 v140, v107, 0, vcc
	v_lshl_add_u64 v[20:21], v[22:23], 0, s[8:9]
	v_cndmask_b32_e64 v144, v106, 0, vcc
	global_load_dwordx4 v[52:55], v[52:53], off offset:2048
	s_nop 0
	global_load_dwordx4 v[60:63], v[20:21], off offset:16
	v_cndmask_b32_e64 v177, v28, 0, vcc
	v_cndmask_b32_e64 v184, v29, 0, vcc
	v_cndmask_b32_e64 v188, v30, 0, vcc
	v_cndmask_b32_e64 v192, v31, 0, vcc
	v_cndmask_b32_e64 v178, v32, 0, s[0:1]
	v_cndmask_b32_e64 v185, v33, 0, s[0:1]
	v_cndmask_b32_e64 v189, v34, 0, s[0:1]
	v_cndmask_b32_e64 v193, v35, 0, s[0:1]
	s_waitcnt vmcnt(19)
	v_cndmask_b32_e64 v141, v111, 0, s[0:1]
	v_cndmask_b32_e64 v145, v110, 0, s[0:1]
	v_cndmask_b32_e64 v149, v109, 0, s[0:1]
	v_cndmask_b32_e64 v169, v108, 0, s[0:1]
	v_xor_b32_e32 v108, 1, v182
	v_lshlrev_b32_e32 v120, 16, v121
	v_and_b32_e32 v121, 0xffff0000, v121
	v_lshlrev_b32_e32 v122, 16, v123
	v_and_b32_e32 v123, 0xffff0000, v123
	v_lshlrev_b32_e32 v124, 16, v125
	v_and_b32_e32 v125, 0xffff0000, v125
	v_lshlrev_b32_e32 v130, 16, v131
	v_and_b32_e32 v131, 0xffff0000, v131
	v_cndmask_b32_e64 v179, v36, 0, s[2:3]
	v_cndmask_b32_e64 v186, v37, 0, s[2:3]
	v_cndmask_b32_e64 v190, v38, 0, s[2:3]
	v_cndmask_b32_e64 v194, v39, 0, s[2:3]
	s_waitcnt vmcnt(18)
	v_cndmask_b32_e64 v142, v11, 0, s[2:3]
	v_cndmask_b32_e64 v146, v10, 0, s[2:3]
	s_waitcnt vmcnt(17)
	v_cndmask_b32_e64 v171, v12, 0, s[4:5]
	v_lshlrev_b32_e32 v12, 2, v3
	v_cndmask_b32_e64 v151, v13, 0, s[4:5]
	s_waitcnt vmcnt(14)
	v_pk_fma_f32 v[104:105], v[90:91], v[104:105], 0 op_sel_hi:[1,1,0]
	v_mov_b32_e32 v13, v0
	v_lshl_add_u64 v[20:21], s[34:35], 0, v[12:13]
	v_cndmask_b32_e64 v147, v14, 0, s[4:5]
	s_waitcnt vmcnt(12)
	v_pk_fma_f32 v[104:105], v[94:95], v[112:113], v[104:105]
	v_add_co_u32_e32 v14, vcc, s62, v20
	v_cndmask_b32_e64 v143, v15, 0, s[4:5]
	s_waitcnt vmcnt(11)
	v_pk_fma_f32 v[104:105], v[98:99], v[114:115], v[104:105]
	v_addc_co_u32_e32 v15, vcc, 0, v21, vcc
	v_cndmask_b32_e64 v137, v18, 0, s[6:7]
	s_waitcnt vmcnt(9)
	v_pk_fma_f32 v[104:105], v[102:103], v[116:117], v[104:105]
	v_add_co_u32_e32 v18, vcc, s25, v20
	v_mul_f32_e32 v3, 0xbfb8aa3b, v105
	v_exp_f32_e32 v107, v3
	v_mul_f32_e32 v3, 0xbfb8aa3b, v104
	v_exp_f32_e32 v106, v3
	v_cndmask_b32_e64 v136, v19, 0, s[6:7]
	v_addc_co_u32_e32 v19, vcc, 0, v21, vcc
	v_pk_add_f32 v[2:3], v[106:107], 1.0 op_sel_hi:[1,0]
	v_cndmask_b32_e64 v150, v9, 0, s[2:3]
	s_nop 0
	v_cndmask_b32_e64 v170, v8, 0, s[2:3]
	v_cndmask_b32_e64 v138, v17, 0, s[6:7]
	v_cndmask_b32_e64 v139, v16, 0, s[6:7]
	global_load_dwordx4 v[8:11], v12, s[34:35] offset:16
	global_load_dwordx4 v[24:27], v12, s[34:35]
	v_lshl_add_u64 v[12:13], v[20:21], 0, s[28:29]
	v_lshl_add_u64 v[16:17], v[20:21], 0, s[48:49]
	v_lshl_add_u64 v[22:23], v[20:21], 0, s[30:31]
	v_add_co_u32_e32 v20, vcc, s26, v20
	s_nop 0
	s_nop 0
	v_addc_co_u32_e32 v21, vcc, 0, v21, vcc
	v_cmp_lt_i32_e32 vcc, v108, v201
	v_pk_fma_f32 v[90:91], v[90:91], v[112:113], 0 op_sel_hi:[1,1,0]
	s_mov_b32 s4, 0x358637bd
	v_cndmask_b32_e32 v108, v182, v108, vcc
	v_lshlrev_b32_e32 v173, 2, v108
	s_nop 0
	s_nop 0
	s_nop 0
	s_nop 0
	s_nop 0
	s_nop 0
	s_nop 0
	s_nop 0
	s_nop 0
	s_nop 0
	v_rcp_f32_e32 v3, v3
	s_nop 0
	s_nop 0
	s_nop 0
	s_nop 0
	s_nop 0
	s_nop 0
	v_lshlrev_b32_e32 v106, 16, v119
	v_and_b32_e32 v107, 0xffff0000, v119
	v_pk_fma_f32 v[106:107], v[88:89], v[106:107], 0 op_sel_hi:[1,1,0]
	s_nop 0
	v_pk_fma_f32 v[106:107], v[92:93], v[120:121], v[106:107]
	s_nop 0
	v_pk_fma_f32 v[106:107], v[96:97], v[122:123], v[106:107]
	v_rcp_f32_e32 v2, v2
	v_pk_fma_f32 v[106:107], v[100:101], v[124:125], v[106:107]
	v_pk_fma_f32 v[90:91], v[94:95], v[114:115], v[90:91]
	v_mul_f32_e32 v108, 0xbfb8aa3b, v106
	v_mul_f32_e32 v109, 0xbfb8aa3b, v107
	v_exp_f32_e32 v108, v108
	v_exp_f32_e32 v109, v109
	v_pk_fma_f32 v[90:91], v[98:99], v[116:117], v[90:91]
	v_lshlrev_b32_e32 v94, 16, v203
	v_and_b32_e32 v95, 0xffff0000, v203
	v_pk_add_f32 v[108:109], v[108:109], 1.0 op_sel_hi:[1,0]
	v_pk_fma_f32 v[94:95], v[102:103], v[94:95], v[90:91]
	s_nop 0
	s_nop 0
	s_nop 0
	s_nop 0
	s_nop 0
	s_nop 0
	s_nop 0
	s_nop 0
	s_nop 0
	s_nop 0
	s_nop 0
	s_nop 0
	v_rcp_f32_e32 v109, v109
	s_nop 0
	s_nop 0
	s_nop 0
	s_nop 0
	s_nop 0
	s_nop 0
	v_lshlrev_b32_e32 v110, 16, v118
	v_and_b32_e32 v111, 0xffff0000, v118
	v_lshlrev_b32_e32 v126, 16, v127
	v_and_b32_e32 v127, 0xffff0000, v127
	v_pk_fma_f32 v[110:111], v[74:75], v[110:111], 0 op_sel_hi:[1,1,0]
	v_lshlrev_b32_e32 v128, 16, v129
	v_and_b32_e32 v129, 0xffff0000, v129
	v_pk_fma_f32 v[110:111], v[78:79], v[126:127], v[110:111]
	s_nop 0
	s_waitcnt vmcnt(7)
	v_pk_fma_f32 v[110:111], v[86:87], v[128:129], v[110:111]
	s_nop 0
	v_pk_fma_f32 v[110:111], v[82:83], v[130:131], v[110:111]
	v_rcp_f32_e32 v108, v108
	v_mul_f32_e32 v118, 0xbfb8aa3b, v110
	v_mul_f32_e32 v119, 0xbfb8aa3b, v111
	v_exp_f32_e32 v118, v118
	v_exp_f32_e32 v119, v119
	v_mul_f32_e32 v90, 0xbfb8aa3b, v95
	v_exp_f32_e32 v91, v90
	v_mul_f32_e32 v90, 0xbfb8aa3b, v94
	v_pk_add_f32 v[118:119], v[118:119], 1.0 op_sel_hi:[1,0]
	v_exp_f32_e32 v90, v90
	s_nop 0
	s_nop 0
	s_nop 0
	s_nop 0
	s_nop 0
	s_nop 0
	s_nop 0
	s_nop 0
	s_nop 0
	s_nop 0
	s_nop 0
	s_nop 0
	v_rcp_f32_e32 v119, v119
	s_nop 0
	s_nop 0
	s_nop 0
	s_nop 0
	s_nop 0
	v_lshlrev_b32_e32 v164, 16, v165
	v_and_b32_e32 v165, 0xffff0000, v165
	s_nop 0
	v_lshlrev_b32_e32 v132, 16, v133
	v_and_b32_e32 v133, 0xffff0000, v133
	v_pk_fma_f32 v[164:165], v[72:73], v[164:165], 0 op_sel_hi:[1,1,0]
	v_lshlrev_b32_e32 v160, 16, v161
	v_and_b32_e32 v161, 0xffff0000, v161
	v_pk_fma_f32 v[164:165], v[76:77], v[132:133], v[164:165]
	v_lshlrev_b32_e32 v162, 16, v163
	v_and_b32_e32 v163, 0xffff0000, v163
	v_pk_fma_f32 v[164:165], v[84:85], v[160:161], v[164:165]
	s_nop 0
	v_pk_fma_f32 v[164:165], v[80:81], v[162:163], v[164:165]
	s_nop 0
	v_mul_f32_e32 v204, 0xbfb8aa3b, v164
	v_mul_f32_e32 v205, 0xbfb8aa3b, v165
	v_exp_f32_e32 v204, v204
	v_exp_f32_e32 v205, v205
	v_rcp_f32_e32 v118, v118
	v_pk_fma_f32 v[88:89], v[88:89], v[120:121], 0 op_sel_hi:[1,1,0]
	v_pk_fma_f32 v[74:75], v[74:75], v[126:127], 0 op_sel_hi:[1,1,0]
	v_pk_add_f32 v[204:205], v[204:205], 1.0 op_sel_hi:[1,0]
	v_pk_fma_f32 v[88:89], v[92:93], v[122:123], v[88:89]
	s_nop 0
	s_nop 0
	v_pk_fma_f32 v[88:89], v[96:97], v[124:125], v[88:89]
	v_lshlrev_b32_e32 v92, 16, v202
	v_and_b32_e32 v93, 0xffff0000, v202
	s_nop 0
	s_nop 0
	s_nop 0
	s_nop 0
	s_nop 0
	s_nop 0
	s_nop 0
	s_nop 0
	s_nop 0
	s_nop 0
	v_rcp_f32_e32 v205, v205
	v_pk_fma_f32 v[92:93], v[100:101], v[92:93], v[88:89]
	s_nop 0
	s_nop 0
	s_nop 0
	s_nop 0
	s_nop 0
	s_nop 0
	s_nop 0
	s_nop 0
	v_pk_add_f32 v[98:99], v[90:91], 1.0 op_sel_hi:[1,0]
	v_mul_f32_e32 v88, 0xbfb8aa3b, v92
	s_nop 0
	s_nop 0
	v_mul_f32_e32 v89, 0xbfb8aa3b, v93
	v_exp_f32_e32 v88, v88
	v_exp_f32_e32 v89, v89
	s_nop 0
	s_nop 0
	s_nop 0
	s_nop 0
	s_nop 0
	s_nop 0
	s_nop 0
	s_nop 0
	s_nop 0
	s_nop 0
	v_rcp_f32_e32 v99, v99
	v_pk_fma_f32 v[74:75], v[78:79], v[128:129], v[74:75]
	s_nop 0
	s_nop 0
	s_nop 0
	s_nop 0
	s_nop 0
	s_nop 0
	s_nop 0
	s_nop 0
	v_pk_add_f32 v[96:97], v[88:89], 1.0 op_sel_hi:[1,0]
	v_rcp_f32_e32 v98, v98
	s_nop 0
	s_nop 0
	v_pk_mul_f32 v[88:89], v[94:95], v[98:99]
	v_pk_fma_f32 v[74:75], v[86:87], v[130:131], v[74:75]
	v_lshlrev_b32_e32 v78, 16, v199
	s_nop 0
	s_nop 0
	s_nop 0
	s_nop 0
	s_nop 0
	s_nop 0
	s_nop 0
	s_nop 0
	s_nop 0
	v_and_b32_e32 v79, 0xffff0000, v199
	v_pk_fma_f32 v[74:75], v[82:83], v[78:79], v[74:75]
	s_nop 0
	v_mul_f32_e32 v78, 0xbfb8aa3b, v74
	v_mul_f32_e32 v79, 0xbfb8aa3b, v75
	v_rcp_f32_e32 v97, v97
	s_nop 0
	v_exp_f32_e32 v78, v78
	v_exp_f32_e32 v79, v79
	s_nop 0
	s_nop 0
	s_nop 0
	s_nop 0
	s_nop 0
	v_pk_add_f32 v[78:79], v[78:79], 1.0 op_sel_hi:[1,0]
	s_nop 0
	s_nop 0
	s_nop 0
	s_nop 0
	v_rcp_f32_e32 v96, v96
	s_nop 0
	v_pk_mul_f32 v[82:83], v[92:93], v[96:97]
	v_pk_fma_f32 v[72:73], v[72:73], v[132:133], 0 op_sel_hi:[1,1,0]
	s_nop 0
	s_nop 0
	s_nop 0
	s_nop 0
	s_nop 0
	v_pk_fma_f32 v[72:73], v[76:77], v[160:161], v[72:73]
	s_nop 0
	s_nop 0
	v_pk_fma_f32 v[72:73], v[84:85], v[162:163], v[72:73]
	v_lshlrev_b32_e32 v76, 16, v196
	v_and_b32_e32 v77, 0xffff0000, v196
	s_nop 0
	v_pk_fma_f32 v[72:73], v[80:81], v[76:77], v[72:73]
	s_nop 0
	v_mul_f32_e32 v76, 0xbfb8aa3b, v72
	v_mul_f32_e32 v77, 0xbfb8aa3b, v73
	v_exp_f32_e32 v76, v76
	v_exp_f32_e32 v77, v77
	s_nop 0
	v_rcp_f32_e32 v79, v79
	s_nop 0
	s_nop 0
	s_nop 0
	s_nop 0
	v_pk_add_f32 v[76:77], v[76:77], 1.0 op_sel_hi:[1,0]
	s_nop 0
	s_nop 0
	s_nop 0
	s_nop 0
	s_nop 0
	s_nop 0
	v_rcp_f32_e32 v78, v78
	s_nop 0
	v_pk_mul_f32 v[80:81], v[74:75], v[78:79]
	s_nop 0
	s_nop 0
	s_nop 0
	s_nop 0
	s_nop 0
	s_nop 0
	s_nop 0
	s_nop 0
	s_nop 0
	s_nop 0
	v_rcp_f32_e32 v77, v77
	v_rcp_f32_e32 v204, v204
	s_nop 0
	s_nop 0
	s_nop 0
	s_nop 0
	s_nop 0
	s_nop 0
	s_nop 0
	s_nop 0
	v_rcp_f32_e32 v76, v76
	v_pk_mul_f32 v[90:91], v[164:165], v[204:205]
	v_pk_mul_f32 v[84:85], v[72:73], v[76:77]
	v_pk_mul_f32 v[110:111], v[110:111], v[118:119]
	v_pk_mul_f32 v[102:103], v[90:91], v[90:91]
	v_pk_mul_f32 v[72:73], v[84:85], v[84:85]
	v_pk_mul_f32 v[118:119], v[110:111], v[110:111]
	v_pk_mul_f32 v[74:75], v[80:81], v[80:81]
	v_mov_b32_e32 v76, v72
	v_mov_b32_e32 v77, v102
	v_mov_b32_e32 v102, v73
	v_pk_mul_f32 v[106:107], v[106:107], v[108:109]
	v_pk_add_f32 v[72:73], v[76:77], v[102:103]
	v_mov_b32_e32 v76, v74
	v_mov_b32_e32 v77, v118
	v_pk_mul_f32 v[108:109], v[106:107], v[106:107]
	v_pk_mul_f32 v[86:87], v[82:83], v[82:83]
	v_pk_add_f32 v[72:73], v[76:77], v[72:73]
	v_mov_b32_e32 v118, v75
	v_pk_mul_f32 v[2:3], v[104:105], v[2:3]
	v_pk_add_f32 v[72:73], v[118:119], v[72:73]
	v_mov_b32_e32 v74, v86
	v_mov_b32_e32 v75, v108
	v_pk_mul_f32 v[104:105], v[2:3], v[2:3]
	v_pk_mul_f32 v[94:95], v[88:89], v[88:89]
	v_pk_add_f32 v[72:73], v[74:75], v[72:73]
	v_mov_b32_e32 v108, v87
	v_pk_add_f32 v[72:73], v[108:109], v[72:73]
	v_mov_b32_e32 v74, v94
	v_mov_b32_e32 v75, v104
	v_pk_add_f32 v[72:73], v[74:75], v[72:73]
	v_mov_b32_e32 v104, v95
	v_pk_add_f32 v[72:73], v[104:105], v[72:73]
	v_xor_b32_e32 v76, 2, v182
	v_cmp_lt_i32_e32 vcc, v76, v201
	s_mov_b32 s0, 0x27ffffc
	v_and_b32_e32 v77, 48, v197
	v_cndmask_b32_e32 v76, v182, v76, vcc
	v_lshlrev_b32_e32 v118, 2, v76
	s_waitcnt lgkmcnt(0)
	s_nop 1
	v_add_f32_dpp v72, v72, v72 quad_perm:[1,0,3,2] row_mask:0xf bank_mask:0xf
	v_add_f32_dpp v73, v73, v73 quad_perm:[1,0,3,2] row_mask:0xf bank_mask:0xf
	v_xor_b32_e32 v76, 4, v182
	v_cmp_lt_i32_e32 vcc, v76, v201
	v_add_u32_e32 v92, 0, v197
	s_add_i32 s25, 0, 0x20500
	v_cndmask_b32_e32 v76, v182, v76, vcc
	v_lshlrev_b32_e32 v119, 2, v76
	s_waitcnt lgkmcnt(0)
	s_nop 1
	v_add_f32_dpp v72, v72, v72 quad_perm:[2,3,0,1] row_mask:0xf bank_mask:0xf
	v_add_f32_dpp v73, v73, v73 quad_perm:[2,3,0,1] row_mask:0xf bank_mask:0xf
	v_xor_b32_e32 v76, 8, v182
	v_cmp_lt_i32_e32 vcc, v76, v201
	global_load_dwordx4 v[28:31], v[14:15], off
	s_nop 0
	global_load_dwordx4 v[12:15], v[12:13], off offset:16
	v_cndmask_b32_e32 v76, v182, v76, vcc
	v_lshlrev_b32_e32 v120, 2, v76
	s_waitcnt lgkmcnt(0)
	s_nop 1
	v_add_f32_dpp v72, v72, v72 row_half_mirror row_mask:0xf bank_mask:0xf
	v_add_f32_dpp v73, v73, v73 row_half_mirror row_mask:0xf bank_mask:0xf
	v_and_or_b32 v76, v198, s0, v200
	v_lshl_or_b32 v121, v76, 6, v77
	v_mad_u64_u32 v[76:77], s[0:1], v183, s54, v[92:93]
	s_waitcnt lgkmcnt(0)
	s_nop 1
	v_add_f32_dpp v72, v72, v72 row_mirror row_mask:0xf bank_mask:0xf
	v_add_f32_dpp v73, v73, v73 row_mirror row_mask:0xf bank_mask:0xf
	global_load_dwordx4 v[32:35], v[18:19], off
	s_nop 0
	global_load_dwordx4 v[16:19], v[16:17], off offset:16
	v_pk_add_f32 v[86:87], v[72:73], s[4:5] op_sel_hi:[1,0]
	global_load_dwordx4 v[36:39], v[20:21], off
	s_nop 0
	global_load_dwordx4 v[20:23], v[22:23], off offset:16
	v_mul_f32_e32 v72, 0x4b800000, v87
	v_cmp_gt_f32_e32 vcc, s51, v87
	v_lshl_add_u32 v77, v183, 2, s25
	s_add_u32 s0, s10, s16
	v_cndmask_b32_e32 v72, v87, v72, vcc
	v_rsq_f32_e32 v72, v72
	v_mul_f32_e32 v87, 0x4b800000, v86
	s_addc_u32 s1, s11, s17
	v_lshlrev_b32_e32 v100, 16, v194
	v_mul_f32_e32 v73, 0x45800000, v72
	v_cndmask_b32_e32 v72, v72, v73, vcc
	v_mul_f32_e32 v72, 0x3db504f3, v72
	v_pk_mul_f32 v[90:91], v[90:91], v[72:73] op_sel_hi:[1,0]
	v_pk_mul_f32 v[94:95], v[110:111], v[72:73] op_sel_hi:[1,0]
	v_pk_mul_f32 v[96:97], v[106:107], v[72:73] op_sel_hi:[1,0]
	v_pk_mul_f32 v[2:3], v[2:3], v[72:73] op_sel_hi:[1,0]
	v_cvt_pk_bf16_f32 v72, v90, v91
	v_cvt_pk_bf16_f32 v73, v94, v95
	v_cvt_pk_bf16_f32 v74, v96, v97
	v_cvt_pk_bf16_f32 v75, v2, v3
	ds_write_b128 v76, v[72:75] offset:17408
	ds_read_b32 v74, v77
	v_cmp_gt_f32_e32 vcc, s51, v86
	v_and_or_b32 v72, v181, 14, v121
	v_lshlrev_b32_e32 v72, 3, v72
	v_cndmask_b32_e32 v86, v86, v87, vcc
	s_waitcnt lgkmcnt(0)
	v_mul_f32_e32 v74, 0x3fb8aa3b, v74
	v_exp_f32_e32 v98, v74
	v_rsq_f32_e32 v86, v86
	v_ashrrev_i32_e32 v73, 31, v72
	v_lshl_add_u64 v[78:79], v[72:73], 1, s[0:1]
	v_pk_mul_f32 v[72:73], v[98:99], v[90:91] op_sel_hi:[0,1]
	v_pk_mul_f32 v[74:75], v[98:99], v[94:95] op_sel_hi:[0,1]
	v_cvt_pk_bf16_f32 v72, v72, v73
	v_cvt_pk_bf16_f32 v73, v74, v75
	v_pk_mul_f32 v[74:75], v[98:99], v[96:97] op_sel_hi:[0,1]
	v_pk_mul_f32 v[2:3], v[98:99], v[2:3] op_sel_hi:[0,1]
	v_cvt_pk_bf16_f32 v74, v74, v75
	v_cvt_pk_bf16_f32 v75, v2, v3
	v_mul_f32_e32 v2, 0x45800000, v86
	v_cndmask_b32_e32 v2, v86, v2, vcc
	v_mul_f32_e32 v2, 0x3db504f3, v2
	v_pk_mul_f32 v[86:87], v[84:85], v[2:3] op_sel_hi:[1,0]
	v_pk_mul_f32 v[84:85], v[80:81], v[2:3] op_sel_hi:[1,0]
	v_pk_mul_f32 v[82:83], v[82:83], v[2:3] op_sel_hi:[1,0]
	v_pk_mul_f32 v[80:81], v[88:89], v[2:3] op_sel_hi:[1,0]
	v_lshlrev_b32_e32 v2, 16, v192
	v_and_b32_e32 v3, 0xffff0000, v192
	v_lshlrev_b32_e32 v98, 16, v193
	v_and_b32_e32 v99, 0xffff0000, v193
	v_pk_fma_f32 v[2:3], v[58:59], v[2:3], 0 op_sel_hi:[1,1,0]
	v_and_b32_e32 v101, 0xffff0000, v194
	s_waitcnt vmcnt(11)
	v_pk_fma_f32 v[2:3], v[66:67], v[98:99], v[2:3]
	v_lshlrev_b32_e32 v102, 16, v195
	v_and_b32_e32 v103, 0xffff0000, v195
	s_waitcnt vmcnt(10)
	v_pk_fma_f32 v[2:3], v[70:71], v[100:101], v[2:3]
	v_or_b32_e32 v77, 1, v181
	s_waitcnt vmcnt(8)
	v_pk_fma_f32 v[94:95], v[62:63], v[102:103], v[2:3]
	v_cvt_pk_bf16_f32 v88, v86, v87
	v_mul_f32_e32 v2, 0xbfb8aa3b, v95
	v_exp_f32_e32 v97, v2
	v_mul_f32_e32 v2, 0xbfb8aa3b, v94
	v_exp_f32_e32 v96, v2
	v_mad_u64_u32 v[2:3], s[2:3], v77, s54, v[92:93]
	v_cvt_pk_bf16_f32 v89, v84, v85
	v_pk_add_f32 v[92:93], v[96:97], 1.0 op_sel_hi:[1,0]
	v_cvt_pk_bf16_f32 v90, v82, v83
	s_nop 0
	s_nop 0
	v_cvt_pk_bf16_f32 v91, v80, v81
	ds_write_b128 v2, v[88:91] offset:17408
	s_nop 0
	s_nop 0
	s_nop 0
	s_nop 0
	s_nop 0
	s_nop 0
	s_nop 0
	s_nop 0
	s_nop 0
	s_nop 0
	v_rcp_f32_e32 v89, v93
	s_nop 0
	s_nop 0
	s_nop 0
	s_nop 0
	s_nop 0
	s_nop 0
	v_lshlrev_b32_e32 v90, 16, v188
	v_and_b32_e32 v91, 0xffff0000, v188
	v_lshlrev_b32_e32 v106, 16, v189
	v_and_b32_e32 v107, 0xffff0000, v189
	v_pk_fma_f32 v[90:91], v[56:57], v[90:91], 0 op_sel_hi:[1,1,0]
	v_lshlrev_b32_e32 v108, 16, v190
	v_and_b32_e32 v109, 0xffff0000, v190
	v_pk_fma_f32 v[90:91], v[64:65], v[106:107], v[90:91]
	v_lshlrev_b32_e32 v110, 16, v191
	v_and_b32_e32 v111, 0xffff0000, v191
	v_pk_fma_f32 v[90:91], v[68:69], v[108:109], v[90:91]
	s_nop 0
	v_pk_fma_f32 v[96:97], v[60:61], v[110:111], v[90:91]
	s_nop 0
	v_mul_f32_e32 v90, 0xbfb8aa3b, v96
	v_mul_f32_e32 v91, 0xbfb8aa3b, v97
	v_exp_f32_e32 v90, v90
	v_exp_f32_e32 v91, v91
	v_rcp_f32_e32 v88, v92
	s_nop 0
	v_pk_mul_f32 v[88:89], v[94:95], v[88:89]
	v_and_b32_e32 v113, 0xffff0000, v185
	v_pk_add_f32 v[104:105], v[90:91], 1.0 op_sel_hi:[1,0]
	v_lshlrev_b32_e32 v114, 16, v186
	s_nop 0
	s_nop 0
	s_nop 0
	s_nop 0
	s_nop 0
	s_nop 0
	s_nop 0
	s_nop 0
	s_nop 0
	s_nop 0
	s_nop 0
	s_nop 0
	v_rcp_f32_e32 v93, v105
	s_nop 0
	s_nop 0
	s_nop 0
	s_nop 0
	s_nop 0
	s_nop 0
	v_lshlrev_b32_e32 v94, 16, v184
	v_and_b32_e32 v95, 0xffff0000, v184
	v_lshlrev_b32_e32 v112, 16, v185
	v_pk_fma_f32 v[94:95], v[42:43], v[94:95], 0 op_sel_hi:[1,1,0]
	v_and_b32_e32 v115, 0xffff0000, v186
	v_pk_fma_f32 v[94:95], v[46:47], v[112:113], v[94:95]
	v_lshlrev_b32_e32 v116, 16, v187
	v_and_b32_e32 v117, 0xffff0000, v187
	v_pk_fma_f32 v[94:95], v[50:51], v[114:115], v[94:95]
	s_nop 0
	v_pk_fma_f32 v[122:123], v[54:55], v[116:117], v[94:95]
	s_nop 0
	v_mul_f32_e32 v94, 0xbfb8aa3b, v122
	v_mul_f32_e32 v95, 0xbfb8aa3b, v123
	v_exp_f32_e32 v94, v94
	v_exp_f32_e32 v95, v95
	v_rcp_f32_e32 v92, v104
	s_nop 0
	v_pk_mul_f32 v[92:93], v[96:97], v[92:93]
	v_and_b32_e32 v127, 0xffff0000, v178
	v_pk_add_f32 v[124:125], v[94:95], 1.0 op_sel_hi:[1,0]
	v_lshlrev_b32_e32 v128, 16, v179
	s_nop 0
	s_nop 0
	s_nop 0
	s_nop 0
	s_nop 0
	s_nop 0
	s_nop 0
	s_nop 0
	s_nop 0
	s_nop 0
	s_nop 0
	s_nop 0
	v_rcp_f32_e32 v97, v125
	s_nop 0
	s_nop 0
	s_nop 0
	s_nop 0
	s_nop 0
	s_nop 0
	v_lshlrev_b32_e32 v104, 16, v177
	v_and_b32_e32 v105, 0xffff0000, v177
	v_lshlrev_b32_e32 v126, 16, v178
	v_pk_fma_f32 v[104:105], v[40:41], v[104:105], 0 op_sel_hi:[1,1,0]
	v_and_b32_e32 v129, 0xffff0000, v179
	v_pk_fma_f32 v[104:105], v[44:45], v[126:127], v[104:105]
	v_lshlrev_b32_e32 v130, 16, v180
	v_and_b32_e32 v131, 0xffff0000, v180
	v_pk_fma_f32 v[104:105], v[48:49], v[128:129], v[104:105]
	s_nop 0
	v_pk_fma_f32 v[132:133], v[52:53], v[130:131], v[104:105]
	s_nop 0
	v_mul_f32_e32 v104, 0xbfb8aa3b, v132
	v_mul_f32_e32 v105, 0xbfb8aa3b, v133
	v_exp_f32_e32 v104, v104
	v_exp_f32_e32 v105, v105
	v_rcp_f32_e32 v96, v124
	s_nop 0
	v_pk_mul_f32 v[96:97], v[122:123], v[96:97]
	v_pk_fma_f32 v[58:59], v[58:59], v[98:99], 0 op_sel_hi:[1,1,0]
	v_pk_add_f32 v[160:161], v[104:105], 1.0 op_sel_hi:[1,0]
	v_pk_fma_f32 v[58:59], v[66:67], v[100:101], v[58:59]
	s_nop 0
	s_nop 0
	v_pk_fma_f32 v[58:59], v[70:71], v[102:103], v[58:59]
	v_lshlrev_b32_e32 v66, 16, v176
	v_and_b32_e32 v67, 0xffff0000, v176
	s_nop 0
	s_nop 0
	s_nop 0
	s_nop 0
	s_nop 0
	s_nop 0
	s_nop 0
	s_nop 0
	s_nop 0
	s_nop 0
	v_pk_fma_f32 v[62:63], v[62:63], v[66:67], v[58:59]
	v_rcp_f32_e32 v123, v161
	s_nop 0
	v_mul_f32_e32 v58, 0xbfb8aa3b, v63
	s_nop 0
	s_nop 0
	v_exp_f32_e32 v59, v58
	v_mul_f32_e32 v58, 0xbfb8aa3b, v62
	s_nop 0
	v_exp_f32_e32 v58, v58
	s_nop 0
	s_nop 0
	s_nop 0
	s_nop 0
	v_pk_add_f32 v[66:67], v[58:59], 1.0 op_sel_hi:[1,0]
	v_pk_fma_f32 v[56:57], v[56:57], v[106:107], 0 op_sel_hi:[1,1,0]
	s_nop 0
	s_nop 0
	v_pk_fma_f32 v[56:57], v[64:65], v[108:109], v[56:57]
	v_lshlrev_b32_e32 v64, 16, v175
	v_pk_fma_f32 v[56:57], v[68:69], v[110:111], v[56:57]
	s_nop 0
	s_nop 0
	s_nop 0
	s_nop 0
	s_nop 0
	s_nop 0
	s_nop 0
	s_nop 0
	s_nop 0
	s_nop 0
	v_and_b32_e32 v65, 0xffff0000, v175
	v_rcp_f32_e32 v67, v67
	s_nop 0
	v_pk_fma_f32 v[60:61], v[60:61], v[64:65], v[56:57]
	s_nop 0
	s_nop 0
	v_mul_f32_e32 v56, 0xbfb8aa3b, v60
	v_mul_f32_e32 v57, 0xbfb8aa3b, v61
	s_nop 0
	v_exp_f32_e32 v56, v56
	v_exp_f32_e32 v57, v57
	s_nop 0
	s_nop 0
	s_nop 0
	s_nop 0
	v_pk_add_f32 v[64:65], v[56:57], 1.0 op_sel_hi:[1,0]
	v_rcp_f32_e32 v66, v66
	s_nop 0
	s_nop 0
	v_pk_mul_f32 v[56:57], v[62:63], v[66:67]
	v_pk_fma_f32 v[42:43], v[42:43], v[112:113], 0 op_sel_hi:[1,1,0]
	v_pk_fma_f32 v[40:41], v[40:41], v[126:127], 0 op_sel_hi:[1,1,0]
	s_nop 0
	s_nop 0
	s_nop 0
	s_nop 0
	s_nop 0
	s_nop 0
	s_nop 0
	s_nop 0
	s_nop 0
	v_pk_fma_f32 v[42:43], v[46:47], v[114:115], v[42:43]
	v_lshlrev_b32_e32 v46, 16, v174
	v_pk_fma_f32 v[42:43], v[50:51], v[116:117], v[42:43]
	v_and_b32_e32 v47, 0xffff0000, v174
	v_pk_fma_f32 v[42:43], v[54:55], v[46:47], v[42:43]
	s_nop 0
	v_mul_f32_e32 v46, 0xbfb8aa3b, v42
	v_mul_f32_e32 v47, 0xbfb8aa3b, v43
	v_rcp_f32_e32 v65, v65
	s_nop 0
	v_exp_f32_e32 v46, v46
	v_exp_f32_e32 v47, v47
	s_nop 0
	s_nop 0
	s_nop 0
	s_nop 0
	s_nop 0
	v_pk_add_f32 v[46:47], v[46:47], 1.0 op_sel_hi:[1,0]
	s_nop 0
	s_nop 0
	s_nop 0
	s_nop 0
	v_rcp_f32_e32 v64, v64
	s_nop 0
	v_pk_mul_f32 v[50:51], v[60:61], v[64:65]
	v_pk_fma_f32 v[40:41], v[44:45], v[128:129], v[40:41]
	s_nop 0
	s_nop 0
	s_nop 0
	s_nop 0
	s_nop 0
	v_pk_fma_f32 v[40:41], v[48:49], v[130:131], v[40:41]
	v_lshlrev_b32_e32 v44, 16, v172
	v_and_b32_e32 v45, 0xffff0000, v172
	s_nop 0
	s_nop 0
	v_pk_fma_f32 v[40:41], v[52:53], v[44:45], v[40:41]
	s_nop 0
	v_mul_f32_e32 v44, 0xbfb8aa3b, v40
	v_mul_f32_e32 v45, 0xbfb8aa3b, v41
	v_exp_f32_e32 v44, v44
	v_exp_f32_e32 v45, v45
	s_nop 0
	s_nop 0
	v_rcp_f32_e32 v47, v47
	s_nop 0
	s_nop 0
	s_nop 0
	v_pk_add_f32 v[44:45], v[44:45], 1.0 op_sel_hi:[1,0]
	s_nop 0
	s_nop 0
	s_nop 0
	s_nop 0
	s_nop 0
	s_nop 0
	s_nop 0
	v_rcp_f32_e32 v46, v46
	s_nop 0
	s_nop 0
	s_nop 0
	s_nop 0
	s_nop 0
	s_nop 0
	s_nop 0
	s_nop 0
	s_nop 0
	s_nop 0
	v_rcp_f32_e32 v45, v45
	v_rcp_f32_e32 v122, v160
	s_nop 0
	s_nop 0
	s_nop 0
	s_nop 0
	s_nop 0
	s_nop 0
	s_nop 0
	s_nop 0
	v_rcp_f32_e32 v44, v44
	v_pk_mul_f32 v[58:59], v[132:133], v[122:123]
	v_pk_mul_f32 v[44:45], v[40:41], v[44:45]
	v_pk_mul_f32 v[70:71], v[58:59], v[58:59]
	v_pk_mul_f32 v[46:47], v[42:43], v[46:47]
	v_pk_mul_f32 v[40:41], v[44:45], v[44:45]
	v_pk_mul_f32 v[104:105], v[96:97], v[96:97]
	v_pk_mul_f32 v[42:43], v[46:47], v[46:47]
	v_mov_b32_e32 v48, v40
	v_mov_b32_e32 v49, v70
	v_mov_b32_e32 v70, v41
	v_pk_add_f32 v[40:41], v[48:49], v[70:71]
	v_mov_b32_e32 v48, v42
	v_mov_b32_e32 v49, v104
	v_pk_mul_f32 v[94:95], v[92:93], v[92:93]
	v_pk_mul_f32 v[54:55], v[50:51], v[50:51]
	v_pk_add_f32 v[40:41], v[48:49], v[40:41]
	v_mov_b32_e32 v104, v43
	v_pk_add_f32 v[40:41], v[104:105], v[40:41]
	v_mov_b32_e32 v42, v54
	v_mov_b32_e32 v43, v94
	v_pk_mul_f32 v[90:91], v[88:89], v[88:89]
	v_pk_mul_f32 v[62:63], v[56:57], v[56:57]
	v_pk_add_f32 v[40:41], v[42:43], v[40:41]
	v_mov_b32_e32 v94, v55
	v_pk_add_f32 v[40:41], v[94:95], v[40:41]
	v_mov_b32_e32 v42, v62
	v_mov_b32_e32 v43, v90
	v_pk_add_f32 v[40:41], v[42:43], v[40:41]
	v_mov_b32_e32 v90, v63
	v_pk_add_f32 v[40:41], v[90:91], v[40:41]
	v_lshl_add_u32 v3, v77, 2, s25
	ds_read_b32 v3, v3
	s_mov_b32 s2, 0x13800000
	v_add_co_u32_e32 v48, vcc, s2, v78
	s_waitcnt lgkmcnt(1)
	s_nop 1
	v_add_f32_dpp v42, v40, v40 quad_perm:[1,0,3,2] row_mask:0xf bank_mask:0xf
	v_add_f32_dpp v43, v41, v41 quad_perm:[1,0,3,2] row_mask:0xf bank_mask:0xf
	v_addc_co_u32_e32 v49, vcc, 0, v79, vcc
	s_waitcnt lgkmcnt(0)
	v_mul_f32_e32 v3, 0x3fb8aa3b, v3
	global_store_dwordx4 v[48:49], v[72:75], off nt
	v_exp_f32_e32 v48, v3
	v_and_or_b32 v3, v77, 15, v121
	v_lshlrev_b32_e32 v66, 16, v144
	s_waitcnt lgkmcnt(0)
	s_nop 1
	v_add_f32_dpp v52, v42, v42 quad_perm:[2,3,0,1] row_mask:0xf bank_mask:0xf
	v_add_f32_dpp v53, v43, v43 quad_perm:[2,3,0,1] row_mask:0xf bank_mask:0xf
	v_pk_mul_f32 v[40:41], v[48:49], v[86:87] op_sel_hi:[0,1]
	v_pk_mul_f32 v[54:55], v[48:49], v[84:85] op_sel_hi:[0,1]
	v_cvt_pk_bf16_f32 v40, v40, v41
	v_cvt_pk_bf16_f32 v41, v54, v55
	v_pk_mul_f32 v[42:43], v[48:49], v[82:83] op_sel_hi:[0,1]
	v_pk_mul_f32 v[48:49], v[48:49], v[80:81] op_sel_hi:[0,1]
	v_cvt_pk_bf16_f32 v42, v42, v43
	v_cvt_pk_bf16_f32 v43, v48, v49
	s_waitcnt lgkmcnt(0)
	s_nop 1
	v_add_f32_dpp v48, v52, v52 row_half_mirror row_mask:0xf bank_mask:0xf
	v_add_f32_dpp v49, v53, v53 row_half_mirror row_mask:0xf bank_mask:0xf
	v_lshlrev_b32_e32 v54, 3, v3
	v_ashrrev_i32_e32 v55, 31, v54
	v_lshl_add_u64 v[54:55], v[54:55], 1, s[0:1]
	v_and_b32_e32 v67, 0xffff0000, v144
	s_waitcnt lgkmcnt(0)
	s_nop 1
	v_add_f32_dpp v48, v48, v48 row_mirror row_mask:0xf bank_mask:0xf
	v_add_f32_dpp v49, v49, v49 row_mirror row_mask:0xf bank_mask:0xf
	v_add_co_u32_e64 v52, s[0:1], s2, v54
	v_pk_add_f32 v[48:49], v[48:49], s[4:5] op_sel_hi:[1,0]
	s_nop 0
	v_addc_co_u32_e64 v53, s[0:1], 0, v55, s[0:1]
	v_mul_f32_e32 v3, 0x4b800000, v49
	v_cmp_gt_f32_e32 vcc, s51, v49
	global_store_dwordx4 v[52:53], v[40:43], off nt
	s_waitcnt vmcnt(9)
	v_pk_fma_f32 v[66:67], v[8:9], v[66:67], 0 op_sel_hi:[1,1,0]
	v_cndmask_b32_e32 v3, v49, v3, vcc
	v_rsq_f32_e32 v3, v3
	v_and_b32_e32 v73, 0xffff0000, v140
	s_bfe_u32 s28, s24, 0x20006
	s_ashr_i32 s26, s24, 7
	v_mul_f32_e32 v40, 0x45800000, v3
	v_cndmask_b32_e32 v40, v3, v40, vcc
	v_mul_f32_e32 v3, 0x4b800000, v48
	v_cmp_gt_f32_e32 vcc, s51, v48
	v_pk_mul_f32 v[42:43], v[58:59], v[40:41] op_sel_hi:[1,0]
	v_pk_mul_f32 v[52:53], v[96:97], v[40:41] op_sel_hi:[1,0]
	v_cndmask_b32_e32 v3, v48, v3, vcc
	v_rsq_f32_e32 v3, v3
	v_pk_mul_f32 v[54:55], v[92:93], v[40:41] op_sel_hi:[1,0]
	v_pk_mul_f32 v[58:59], v[88:89], v[40:41] op_sel_hi:[1,0]
	v_cvt_pk_bf16_f32 v40, v42, v43
	v_cvt_pk_bf16_f32 v41, v52, v53
	v_cvt_pk_bf16_f32 v42, v54, v55
	v_cvt_pk_bf16_f32 v43, v58, v59
	ds_write_b128 v76, v[40:43]
	v_mul_f32_e32 v40, 0x45800000, v3
	v_cndmask_b32_e32 v48, v3, v40, vcc
	v_pk_mul_f32 v[54:55], v[46:47], v[48:49] op_sel_hi:[1,0]
	v_lshlrev_b32_e32 v46, 16, v168
	v_and_b32_e32 v47, 0xffff0000, v168
	v_lshlrev_b32_e32 v40, 16, v169
	v_and_b32_e32 v41, 0xffff0000, v169
	s_waitcnt vmcnt(8)
	v_pk_fma_f32 v[46:47], v[24:25], v[46:47], 0 op_sel_hi:[1,1,0]
	v_lshlrev_b32_e32 v42, 16, v170
	v_and_b32_e32 v43, 0xffff0000, v170
	s_waitcnt vmcnt(7)
	v_pk_fma_f32 v[46:47], v[28:29], v[40:41], v[46:47]
	v_pk_mul_f32 v[52:53], v[44:45], v[48:49] op_sel_hi:[1,0]
	v_lshlrev_b32_e32 v44, 16, v171
	v_and_b32_e32 v45, 0xffff0000, v171
	s_waitcnt vmcnt(5)
	v_pk_fma_f32 v[46:47], v[32:33], v[42:43], v[46:47]
	v_pk_mul_f32 v[50:51], v[50:51], v[48:49] op_sel_hi:[1,0]
	s_waitcnt vmcnt(3)
	v_pk_fma_f32 v[58:59], v[36:37], v[44:45], v[46:47]
	v_cvt_pk_bf16_f32 v46, v52, v53
	v_mul_f32_e32 v3, 0xbfb8aa3b, v58
	v_exp_f32_e32 v60, v3
	v_mul_f32_e32 v3, 0xbfb8aa3b, v59
	v_exp_f32_e32 v61, v3
	v_cvt_pk_bf16_f32 v47, v54, v55
	v_pk_mul_f32 v[56:57], v[56:57], v[48:49] op_sel_hi:[1,0]
	v_cvt_pk_bf16_f32 v48, v50, v51
	v_pk_add_f32 v[52:53], v[60:61], 1.0 op_sel_hi:[1,0]
	v_cvt_pk_bf16_f32 v49, v56, v57
	s_nop 0
	s_nop 0
	ds_write_b128 v2, v[46:49]
	v_and_b32_e32 v55, 0xffff0000, v148
	s_nop 0
	s_nop 0
	s_nop 0
	s_nop 0
	s_nop 0
	s_nop 0
	s_nop 0
	s_nop 0
	s_nop 0
	v_lshlrev_b32_e32 v54, 16, v148
	v_lshlrev_b32_e32 v46, 16, v149
	v_and_b32_e32 v47, 0xffff0000, v149
	v_pk_fma_f32 v[54:55], v[26:27], v[54:55], 0 op_sel_hi:[1,1,0]
	s_nop 0
	v_lshlrev_b32_e32 v48, 16, v150
	v_and_b32_e32 v49, 0xffff0000, v150
	v_pk_fma_f32 v[54:55], v[30:31], v[46:47], v[54:55]
	v_lshlrev_b32_e32 v50, 16, v151
	v_and_b32_e32 v51, 0xffff0000, v151
	v_pk_fma_f32 v[54:55], v[34:35], v[48:49], v[54:55]
	v_rcp_f32_e32 v53, v53
	v_pk_fma_f32 v[60:61], v[38:39], v[50:51], v[54:55]
	s_nop 0
	v_mul_f32_e32 v54, 0xbfb8aa3b, v60
	v_mul_f32_e32 v55, 0xbfb8aa3b, v61
	v_exp_f32_e32 v54, v54
	v_exp_f32_e32 v55, v55
	s_nop 0
	s_nop 0
	s_nop 0
	s_nop 0
	s_nop 0
	v_pk_add_f32 v[62:63], v[54:55], 1.0 op_sel_hi:[1,0]
	s_nop 0
	s_nop 0
	s_nop 0
	s_nop 0
	v_rcp_f32_e32 v52, v52
	s_nop 0
	v_pk_mul_f32 v[64:65], v[58:59], v[52:53]
	s_nop 0
	s_nop 0
	s_nop 0
	s_nop 0
	s_nop 0
	s_nop 0
	s_nop 0
	s_nop 0
	v_lshlrev_b32_e32 v52, 16, v145
	v_and_b32_e32 v53, 0xffff0000, v145
	s_nop 0
	v_lshlrev_b32_e32 v54, 16, v146
	v_and_b32_e32 v55, 0xffff0000, v146
	v_pk_fma_f32 v[66:67], v[12:13], v[52:53], v[66:67]
	s_nop 0
	v_lshlrev_b32_e32 v56, 16, v147
	v_and_b32_e32 v57, 0xffff0000, v147
	v_pk_fma_f32 v[66:67], v[16:17], v[54:55], v[66:67]
	v_rcp_f32_e32 v59, v63
	s_waitcnt vmcnt(2)
	v_pk_fma_f32 v[66:67], v[20:21], v[56:57], v[66:67]
	s_nop 0
	v_mul_f32_e32 v68, 0xbfb8aa3b, v66
	v_mul_f32_e32 v69, 0xbfb8aa3b, v67
	v_exp_f32_e32 v68, v68
	v_exp_f32_e32 v69, v69
	s_nop 0
	s_nop 0
	s_nop 0
	s_nop 0
	v_pk_add_f32 v[68:69], v[68:69], 1.0 op_sel_hi:[1,0]
	s_nop 0
	s_nop 0
	s_nop 0
	s_nop 0
	s_nop 0
	v_rcp_f32_e32 v58, v62
	s_nop 0
	s_nop 0
	s_nop 0
	v_pk_mul_f32 v[62:63], v[60:61], v[58:59]
	s_nop 0
	s_nop 0
	s_nop 0
	s_nop 0
	s_nop 0
	v_lshlrev_b32_e32 v72, 16, v140
	v_lshlrev_b32_e32 v58, 16, v141
	v_and_b32_e32 v59, 0xffff0000, v141
	v_pk_fma_f32 v[72:73], v[10:11], v[72:73], 0 op_sel_hi:[1,1,0]
	s_nop 0
	v_lshlrev_b32_e32 v60, 16, v142
	v_and_b32_e32 v61, 0xffff0000, v142
	v_pk_fma_f32 v[72:73], v[14:15], v[58:59], v[72:73]
	s_nop 0
	v_lshlrev_b32_e32 v70, 16, v143
	v_and_b32_e32 v71, 0xffff0000, v143
	v_pk_fma_f32 v[72:73], v[18:19], v[60:61], v[72:73]
	v_rcp_f32_e32 v69, v69
	v_pk_fma_f32 v[72:73], v[22:23], v[70:71], v[72:73]
	s_nop 0
	v_mul_f32_e32 v74, 0xbfb8aa3b, v73
	v_exp_f32_e32 v75, v74
	v_mul_f32_e32 v74, 0xbfb8aa3b, v72
	v_exp_f32_e32 v74, v74
	s_nop 0
	s_nop 0
	s_nop 0
	s_nop 0
	s_nop 0
	v_pk_add_f32 v[74:75], v[74:75], 1.0 op_sel_hi:[1,0]
	s_nop 0
	s_nop 0
	s_nop 0
	s_nop 0
	v_rcp_f32_e32 v68, v68
	s_nop 0
	v_pk_mul_f32 v[66:67], v[66:67], v[68:69]
	s_nop 0
	s_nop 0
	s_nop 0
	s_nop 0
	s_nop 0
	s_nop 0
	s_nop 0
	s_nop 0
	s_nop 0
	s_nop 0
	v_rcp_f32_e32 v69, v75
	v_pk_fma_f32 v[24:25], v[24:25], v[40:41], 0 op_sel_hi:[1,1,0]
	s_nop 0
	s_nop 0
	s_nop 0
	s_nop 0
	s_nop 0
	s_nop 0
	v_pk_fma_f32 v[24:25], v[28:29], v[42:43], v[24:25]
	s_nop 0
	v_pk_fma_f32 v[24:25], v[32:33], v[44:45], v[24:25]
	v_lshlrev_b32_e32 v28, 16, v139
	v_and_b32_e32 v29, 0xffff0000, v139
	s_nop 0
	v_pk_fma_f32 v[24:25], v[36:37], v[28:29], v[24:25]
	v_rcp_f32_e32 v68, v74
	v_mul_f32_e32 v3, 0xbfb8aa3b, v24
	v_exp_f32_e32 v28, v3
	v_mul_f32_e32 v3, 0xbfb8aa3b, v25
	v_exp_f32_e32 v29, v3
	v_pk_mul_f32 v[32:33], v[72:73], v[68:69]
	v_pk_fma_f32 v[26:27], v[26:27], v[46:47], 0 op_sel_hi:[1,1,0]
	v_cvt_pk_bf16_f32 v43, v32, v33
	v_pk_add_f32 v[28:29], v[28:29], 1.0 op_sel_hi:[1,0]
	v_pk_fma_f32 v[26:27], v[30:31], v[48:49], v[26:27]
	s_nop 0
	s_nop 0
	v_pk_fma_f32 v[26:27], v[34:35], v[50:51], v[26:27]
	v_lshlrev_b32_e32 v30, 16, v138
	v_and_b32_e32 v31, 0xffff0000, v138
	s_nop 0
	s_nop 0
	s_nop 0
	s_nop 0
	s_nop 0
	s_nop 0
	s_nop 0
	s_nop 0
	s_nop 0
	v_pk_fma_f32 v[26:27], v[38:39], v[30:31], v[26:27]
	s_nop 0
	v_mul_f32_e32 v30, 0xbfb8aa3b, v26
	v_mul_f32_e32 v31, 0xbfb8aa3b, v27
	v_rcp_f32_e32 v29, v29
	s_nop 0
	v_exp_f32_e32 v30, v30
	v_exp_f32_e32 v31, v31
	s_nop 0
	s_nop 0
	s_nop 0
	s_nop 0
	s_nop 0
	v_pk_add_f32 v[30:31], v[30:31], 1.0 op_sel_hi:[1,0]
	s_nop 0
	s_nop 0
	s_nop 0
	s_nop 0
	v_rcp_f32_e32 v28, v28
	s_nop 0
	v_pk_mul_f32 v[24:25], v[24:25], v[28:29]
	s_nop 0
	s_nop 0
	s_nop 0
	s_nop 0
	v_pk_fma_f32 v[8:9], v[8:9], v[52:53], 0 op_sel_hi:[1,1,0]
	s_nop 0
	v_pk_fma_f32 v[8:9], v[12:13], v[54:55], v[8:9]
	s_nop 0
	v_pk_fma_f32 v[8:9], v[16:17], v[56:57], v[8:9]
	v_lshlrev_b32_e32 v12, 16, v137
	v_and_b32_e32 v13, 0xffff0000, v137
	s_nop 0
	s_nop 0
	v_pk_fma_f32 v[8:9], v[20:21], v[12:13], v[8:9]
	s_nop 0
	v_mul_f32_e32 v12, 0xbfb8aa3b, v8
	v_mul_f32_e32 v13, 0xbfb8aa3b, v9
	v_exp_f32_e32 v12, v12
	v_exp_f32_e32 v13, v13
	s_nop 0
	v_rcp_f32_e32 v29, v31
	s_nop 0
	s_nop 0
	s_nop 0
	v_pk_add_f32 v[12:13], v[12:13], 1.0 op_sel_hi:[1,0]
	s_nop 0
	s_nop 0
	s_nop 0
	s_nop 0
	s_nop 0
	s_nop 0
	s_nop 0
	v_rcp_f32_e32 v28, v30
	s_nop 0
	s_nop 0
	s_nop 0
	v_pk_mul_f32 v[16:17], v[26:27], v[28:29]
	s_nop 0
	s_nop 0
	v_pk_fma_f32 v[10:11], v[10:11], v[58:59], 0 op_sel_hi:[1,1,0]
	s_nop 0
	v_pk_fma_f32 v[10:11], v[14:15], v[60:61], v[10:11]
	s_nop 0
	s_nop 0
	v_pk_fma_f32 v[10:11], v[18:19], v[70:71], v[10:11]
	v_lshlrev_b32_e32 v14, 16, v136
	v_and_b32_e32 v15, 0xffff0000, v136
	s_nop 0
	v_pk_fma_f32 v[10:11], v[22:23], v[14:15], v[10:11]
	s_nop 0
	v_mul_f32_e32 v14, 0xbfb8aa3b, v11
	v_exp_f32_e32 v15, v14
	v_mul_f32_e32 v14, 0xbfb8aa3b, v10
	v_exp_f32_e32 v14, v14
	v_rcp_f32_e32 v13, v13
	s_nop 0
	s_nop 0
	s_nop 0
	s_nop 0
	s_nop 0
	v_pk_add_f32 v[14:15], v[14:15], 1.0 op_sel_hi:[1,0]
	s_nop 0
	s_nop 0
	s_nop 0
	s_nop 0
	s_nop 0
	v_rcp_f32_e32 v12, v12
	s_nop 0
	s_nop 0
	s_nop 0
	v_pk_mul_f32 v[12:13], v[8:9], v[12:13]
	s_nop 0
	s_nop 0
	s_nop 0
	s_nop 0
	s_nop 0
	s_nop 0
	s_nop 0
	v_rcp_f32_e32 v9, v15
	s_lshl_b32 s29, s28, 4
	s_nop 0
	s_nop 0
	s_nop 0
	s_nop 0
	s_nop 0
	s_nop 0
	s_nop 0
	s_nop 0
	v_rcp_f32_e32 v8, v14
	s_nop 0
	v_pk_mul_f32 v[14:15], v[10:11], v[8:9]
	v_cvt_pk_bf16_f32 v8, v24, v25
	v_cvt_pk_bf16_f32 v9, v16, v17
	v_cvt_pk_bf16_f32 v10, v12, v13
	v_cvt_pk_bf16_f32 v11, v14, v15
	v_and_b32_e32 v3, 48, v134
	ds_write_b128 v2, v[8:11] offset:34816
	s_and_b32 s27, s26, -2
	v_or_b32_e32 v2, s29, v1
	v_add_u32_e32 v48, 0, v3
	v_cvt_pk_bf16_f32 v40, v64, v65
	v_cvt_pk_bf16_f32 v41, v62, v63
	v_cvt_pk_bf16_f32 v42, v66, v67
	v_mad_u32_u24 v55, v2, s54, v48
	v_lshl_or_b32 v59, s27, 4, v1
	ds_write_b128 v76, v[40:43] offset:34816
	s_waitcnt lgkmcnt(0)
	s_barrier
	s_lshr_b32 s0, s24, 6
	s_and_b32 s1, s0, 3
	s_lshr_b32 s2, s0, 2
	s_lshl_b32 s2, s2, 1
	v_lshrrev_b32_e32 v3, 4, v134
	v_mul_u32_u24_e32 v4, 0x110, v1
	v_lshl_add_u32 v4, v3, 4, v4
	s_mul_i32 s3, s1, 0x1100
	s_mul_i32 s4, s2, 0x1100
	v_add_u32_e32 v2, s3, v4
	v_add_u32_e32 v4, s4, v4
	s_lshl_b32 s5, s1, 6
	s_add_u32 s5, s5, 0x20500
	v_lshl_add_u32 v5, v3, 4, s5
	s_lshl_b32 s6, s2, 6
	s_add_u32 s6, s6, 0x20500
	v_lshl_add_u32 v6, v1, 2, s6
	v_mul_u32_u24_e32 v7, 0x110, v1
	v_lshl_add_u32 v7, v3, 4, v7
	s_lshl_b32 s7, s1, 6
	s_add_u32 s7, s7, s4
	s_add_u32 s7, s7, 0xcc00
	v_add_u32_e32 v7, s7, v7
	v_mul_u32_u24_e32 v9, 0x240, v3
	v_lshl_add_u32 v9, v1, 1, v9
	s_mul_i32 s26, s1, 0x900
	s_lshl_b32 s27, s2, 5
	s_add_u32 s26, s26, s27
	s_add_u32 s26, s26, 0x11000
	v_add_u32_e32 v9, s26, v9
	v_lshrrev_b32_e32 v10, 1, v3
	v_lshlrev_b32_e32 v10, 8, v10
	v_lshl_add_u32 v10, v1, 4, v10
	v_and_b32_e32 v11, 1, v3
	v_lshl_add_u32 v10, v11, 3, v10
	s_lshl_b32 s27, s2, 11
	s_lshl_b32 s28, s1, 9
	s_add_u32 s27, s27, s28
	v_add_u32_e32 v10, s27, v10
	s_add_u32 s26, s10, s18
	s_addc_u32 s27, s11, s19
	s_lshl_b32 s28, s2, 4
	s_lshl_b32 s29, s1, 4
	s_sub_i32 s28, s28, s29
	v_lshlrev_b32_e32 v11, 2, v3
	v_sub_u32_e32 v11, v1, v11
	v_add_u32_e32 v11, s28, v11
	v_add_u32_e32 v70, 16, v11
	ds_read_b128 v[60:63], v5
	ds_read_b128 v[64:67], v5 offset:256
	ds_read_b32 v68, v6
	ds_read_b32 v69, v6 offset:64
	ds_read_b128 v[12:15], v2 offset:0
	ds_read_b128 v[28:31], v4 offset:0
	ds_read_b128 v[44:47], v4 offset:17408
	ds_read_b128 v[16:19], v2 offset:64
	ds_read_b128 v[32:35], v4 offset:64
	ds_read_b128 v[48:51], v4 offset:17472
	ds_read_b128 v[20:23], v2 offset:128
	ds_read_b128 v[36:39], v4 offset:128
	ds_read_b128 v[52:55], v4 offset:17536
	ds_read_b128 v[24:27], v2 offset:192
	ds_read_b128 v[40:43], v4 offset:192
	ds_read_b128 v[56:59], v4 offset:17600
	ds_read_b128 v[136:139], v4 offset:4352
	ds_read_b128 v[168:171], v4 offset:21760
	ds_read_b128 v[140:143], v4 offset:4416
	ds_read_b128 v[172:175], v4 offset:21824
	ds_read_b128 v[144:147], v4 offset:4480
	ds_read_b128 v[176:179], v4 offset:21888
	ds_read_b128 v[148:151], v4 offset:4544
	ds_read_b128 v[184:187], v4 offset:21952
	s_waitcnt lgkmcnt(14)
	v_mfma_f32_16x16x32_bf16 v[160:163], v[12:15], v[28:31], 0
	v_mfma_f32_16x16x32_bf16 v[200:203], v[12:15], v[44:47], 0
	s_waitcnt lgkmcnt(14)
	v_mfma_f32_16x16x32_bf16 v[160:163], v[16:19], v[32:35], v[160:163]
	v_mfma_f32_16x16x32_bf16 v[200:203], v[16:19], v[48:51], v[200:203]
	s_waitcnt lgkmcnt(11)
	v_mfma_f32_16x16x32_bf16 v[160:163], v[20:23], v[36:39], v[160:163]
	v_mfma_f32_16x16x32_bf16 v[200:203], v[20:23], v[52:55], v[200:203]
	s_waitcnt lgkmcnt(8)
	v_mfma_f32_16x16x32_bf16 v[160:163], v[24:27], v[40:43], v[160:163]
	v_mfma_f32_16x16x32_bf16 v[200:203], v[24:27], v[56:59], v[200:203]
	s_waitcnt lgkmcnt(6)
	v_mfma_f32_16x16x32_bf16 v[234:237], v[12:15], v[136:139], 0
	v_mfma_f32_16x16x32_bf16 v[238:241], v[12:15], v[168:171], 0
	s_waitcnt lgkmcnt(4)
	v_mfma_f32_16x16x32_bf16 v[234:237], v[16:19], v[140:143], v[234:237]
	v_mfma_f32_16x16x32_bf16 v[238:241], v[16:19], v[172:175], v[238:241]
	s_waitcnt lgkmcnt(2)
	v_mfma_f32_16x16x32_bf16 v[234:237], v[20:23], v[144:147], v[234:237]
	v_mfma_f32_16x16x32_bf16 v[238:241], v[20:23], v[176:179], v[238:241]
	s_waitcnt lgkmcnt(0)
	v_mfma_f32_16x16x32_bf16 v[234:237], v[24:27], v[148:151], v[234:237]
	v_mfma_f32_16x16x32_bf16 v[238:241], v[24:27], v[184:187], v[238:241]
	v_cmp_lt_i32_e64 s[0:1], v11, 0
	v_cmp_lt_i32_e64 s[2:3], v11, 1
	v_cmp_lt_i32_e64 s[4:5], v11, 2
	v_cmp_lt_i32_e64 s[6:7], v11, 3
	v_cmp_lt_i32_e64 s[28:29], v70, 0
	v_cmp_lt_i32_e64 s[30:31], v70, 1
	v_cmp_lt_i32_e64 s[32:33], v70, 2
	v_cmp_lt_i32_e64 s[34:35], v70, 3
	v_sub_f32_e32 v70, v60, v68
	v_sub_f32_e32 v164, v68, v60
	v_sub_f32_e32 v71, v61, v68
	v_sub_f32_e32 v165, v68, v61
	v_sub_f32_e32 v72, v62, v68
	v_sub_f32_e32 v180, v68, v62
	v_sub_f32_e32 v73, v63, v68
	v_sub_f32_e32 v181, v68, v63
	v_mul_f32_e32 v70, 0x3fb8aa3b, v70
	v_mul_f32_e32 v164, 0x3fb8aa3b, v164
	v_mul_f32_e32 v71, 0x3fb8aa3b, v71
	v_mul_f32_e32 v165, 0x3fb8aa3b, v165
	v_mul_f32_e32 v72, 0x3fb8aa3b, v72
	v_mul_f32_e32 v180, 0x3fb8aa3b, v180
	v_mul_f32_e32 v73, 0x3fb8aa3b, v73
	v_mul_f32_e32 v181, 0x3fb8aa3b, v181
	v_exp_f32_e32 v70, v70
	v_exp_f32_e32 v164, v164
	v_exp_f32_e32 v71, v71
	v_exp_f32_e32 v165, v165
	v_exp_f32_e32 v72, v72
	v_exp_f32_e32 v180, v180
	v_exp_f32_e32 v73, v73
	v_exp_f32_e32 v181, v181
	v_mul_f32_e32 v160, v160, v70
	v_mul_f32_e32 v200, v200, v164
	v_mul_f32_e32 v161, v161, v71
	v_mul_f32_e32 v201, v201, v165
	v_mul_f32_e32 v162, v162, v72
	v_mul_f32_e32 v202, v202, v180
	v_mul_f32_e32 v163, v163, v73
	v_mul_f32_e32 v203, v203, v181
	v_mul_f32_e32 v160, v64, v160
	v_mul_f32_e32 v161, v65, v161
	v_mul_f32_e32 v162, v66, v162
	v_mul_f32_e32 v163, v67, v163
	v_cndmask_b32_e64 v160, 0, v160, s[0:1]
	v_cndmask_b32_e64 v200, v200, 0, s[0:1]
	v_cndmask_b32_e64 v161, 0, v161, s[2:3]
	v_cndmask_b32_e64 v201, v201, 0, s[2:3]
	v_cndmask_b32_e64 v162, 0, v162, s[4:5]
	v_cndmask_b32_e64 v202, v202, 0, s[4:5]
	v_cndmask_b32_e64 v163, 0, v163, s[6:7]
	v_cndmask_b32_e64 v203, v203, 0, s[6:7]
	ds_write_b128 v7, v[160:163]
	v_cvt_pk_bf16_f32 v204, v160, v161
	v_cvt_pk_bf16_f32 v205, v162, v163
	ds_write_b16 v9, v204
	ds_write_b16_d16_hi v9, v204 offset:144
	ds_write_b16 v9, v205 offset:288
	ds_write_b16_d16_hi v9, v205 offset:432
	v_cvt_pk_bf16_f32 v200, v200, v201
	v_cvt_pk_bf16_f32 v201, v202, v203
	global_store_dwordx2 v10, v[200:201], s[26:27] nt
	v_sub_f32_e32 v70, v60, v69
	v_sub_f32_e32 v164, v69, v60
	v_sub_f32_e32 v71, v61, v69
	v_sub_f32_e32 v165, v69, v61
	v_sub_f32_e32 v72, v62, v69
	v_sub_f32_e32 v180, v69, v62
	v_sub_f32_e32 v73, v63, v69
	v_sub_f32_e32 v181, v69, v63
	v_mul_f32_e32 v70, 0x3fb8aa3b, v70
	v_mul_f32_e32 v164, 0x3fb8aa3b, v164
	v_mul_f32_e32 v71, 0x3fb8aa3b, v71
	v_mul_f32_e32 v165, 0x3fb8aa3b, v165
	v_mul_f32_e32 v72, 0x3fb8aa3b, v72
	v_mul_f32_e32 v180, 0x3fb8aa3b, v180
	v_mul_f32_e32 v73, 0x3fb8aa3b, v73
	v_mul_f32_e32 v181, 0x3fb8aa3b, v181
	v_exp_f32_e32 v70, v70
	v_exp_f32_e32 v164, v164
	v_exp_f32_e32 v71, v71
	v_exp_f32_e32 v165, v165
	v_exp_f32_e32 v72, v72
	v_exp_f32_e32 v180, v180
	v_exp_f32_e32 v73, v73
	v_exp_f32_e32 v181, v181
	v_mul_f32_e32 v234, v234, v70
	v_mul_f32_e32 v238, v238, v164
	v_mul_f32_e32 v235, v235, v71
	v_mul_f32_e32 v239, v239, v165
	v_mul_f32_e32 v236, v236, v72
	v_mul_f32_e32 v240, v240, v180
	v_mul_f32_e32 v237, v237, v73
	v_mul_f32_e32 v241, v241, v181
	v_mul_f32_e32 v234, v64, v234
	v_mul_f32_e32 v235, v65, v235
	v_mul_f32_e32 v236, v66, v236
	v_mul_f32_e32 v237, v67, v237
	v_cndmask_b32_e64 v234, 0, v234, s[28:29]
	v_cndmask_b32_e64 v238, v238, 0, s[28:29]
	v_cndmask_b32_e64 v235, 0, v235, s[30:31]
	v_cndmask_b32_e64 v239, v239, 0, s[30:31]
	v_cndmask_b32_e64 v236, 0, v236, s[32:33]
	v_cndmask_b32_e64 v240, v240, 0, s[32:33]
	v_cndmask_b32_e64 v237, 0, v237, s[34:35]
	v_cndmask_b32_e64 v241, v241, 0, s[34:35]
	ds_write_b128 v7, v[234:237] offset:4352
	v_cvt_pk_bf16_f32 v246, v234, v235
	v_cvt_pk_bf16_f32 v247, v236, v237
	ds_write_b16 v9, v246 offset:32
	ds_write_b16_d16_hi v9, v246 offset:176
	ds_write_b16 v9, v247 offset:320
	ds_write_b16_d16_hi v9, v247 offset:464
	v_cvt_pk_bf16_f32 v238, v238, v239
	v_cvt_pk_bf16_f32 v239, v240, v241
	global_store_dwordx2 v10, v[238:239], s[26:27] offset:2048 nt
	s_waitcnt lgkmcnt(0)
	s_barrier
	v_readfirstlane_b32 s26, v135
	s_lshr_b32 s26, s26, 6
	s_cmp_eq_u32 s26, 0
	s_cbranch_scc1 .Lpd_inv
	s_cmp_lt_u32 s26, 4
	s_cbranch_scc1 .Lpd_done
	s_lshr_b32 s27, s26, 1
	s_and_b32 s27, s27, 1
	s_and_b32 s28, s26, 1
	s_lshl_b32 s28, s28, 6
	v_and_b32_e32 v4, 63, v135
	v_add_u32_e32 v5, s28, v4
	s_mul_i32 s29, s27, 0x2200
	v_lshl_add_u32 v6, v5, 1, s29
	s_lshl_b32 s30, s27, 7
	s_add_u32 s30, s30, s25
	v_and_b32_e32 v7, 31, v135
	v_lshl_add_u32 v7, v7, 2, s30
	v_mov_b32_e32 v9, s25
	ds_read_b32 v10, v7
	ds_read_b32 v11, v9 offset:252
	ds_read_u16 v136, v6
	ds_read_u16 v137, v6 offset:272
	ds_read_u16 v138, v6 offset:544
	ds_read_u16 v139, v6 offset:816
	ds_read_u16 v140, v6 offset:1088
	ds_read_u16 v141, v6 offset:1360
	ds_read_u16 v142, v6 offset:1632
	ds_read_u16 v143, v6 offset:1904
	ds_read_u16 v144, v6 offset:2176
	ds_read_u16 v145, v6 offset:2448
	ds_read_u16 v146, v6 offset:2720
	ds_read_u16 v147, v6 offset:2992
	ds_read_u16 v148, v6 offset:3264
	ds_read_u16 v149, v6 offset:3536
	ds_read_u16 v150, v6 offset:3808
	ds_read_u16 v151, v6 offset:4080
	ds_read_u16 v184, v6 offset:4352
	ds_read_u16 v185, v6 offset:4624
	ds_read_u16 v186, v6 offset:4896
	ds_read_u16 v187, v6 offset:5168
	ds_read_u16 v188, v6 offset:5440
	ds_read_u16 v189, v6 offset:5712
	ds_read_u16 v190, v6 offset:5984
	ds_read_u16 v191, v6 offset:6256
	ds_read_u16 v192, v6 offset:6528
	ds_read_u16 v193, v6 offset:6800
	ds_read_u16 v194, v6 offset:7072
	ds_read_u16 v195, v6 offset:7344
	ds_read_u16 v196, v6 offset:7616
	ds_read_u16 v197, v6 offset:7888
	ds_read_u16 v198, v6 offset:8160
	ds_read_u16 v199, v6 offset:8432
	v_lshrrev_b32_e32 v2, 4, v5
	v_lshl_add_u32 v2, v2, 1, s27
	v_lshlrev_b32_e32 v2, 10, v2
	v_and_b32_e32 v3, 15, v5
	v_lshl_add_u32 v2, v3, 4, v2
	s_add_u32 s4, s10, s16
	s_addc_u32 s5, s11, s17
	s_add_u32 s4, s4, 0x15800000
	s_addc_u32 s5, s5, 0
	s_waitcnt lgkmcnt(14)
	v_sub_f32_e32 v10, v11, v10
	v_mul_f32_e32 v10, 0x3fb8aa3b, v10
	v_exp_f32_e32 v10, v10
	s_nop 1
	s_waitcnt lgkmcnt(14)
	v_readlane_b32 s32, v10, 0
	v_readlane_b32 s33, v10, 1
	v_readlane_b32 s34, v10, 2
	v_readlane_b32 s35, v10, 3
	v_readlane_b32 s36, v10, 4
	v_readlane_b32 s37, v10, 5
	v_readlane_b32 s38, v10, 6
	v_readlane_b32 s39, v10, 7
	v_lshlrev_b32_e32 v136, 16, v136
	v_lshlrev_b32_e32 v137, 16, v137
	v_lshlrev_b32_e32 v138, 16, v138
	v_lshlrev_b32_e32 v139, 16, v139
	v_lshlrev_b32_e32 v140, 16, v140
	v_lshlrev_b32_e32 v141, 16, v141
	v_lshlrev_b32_e32 v142, 16, v142
	v_lshlrev_b32_e32 v143, 16, v143
	v_mul_f32_e32 v136, s32, v136
	v_mul_f32_e32 v137, s33, v137
	v_mul_f32_e32 v138, s34, v138
	v_mul_f32_e32 v139, s35, v139
	v_mul_f32_e32 v140, s36, v140
	v_mul_f32_e32 v141, s37, v141
	v_mul_f32_e32 v142, s38, v142
	v_mul_f32_e32 v143, s39, v143
	v_cvt_pk_bf16_f32 v12, v136, v137
	v_cvt_pk_bf16_f32 v13, v138, v139
	v_cvt_pk_bf16_f32 v14, v140, v141
	v_cvt_pk_bf16_f32 v15, v142, v143
	global_store_dwordx4 v2, v[12:15], s[4:5] nt
	s_waitcnt lgkmcnt(14)
	v_readlane_b32 s32, v10, 8
	v_readlane_b32 s33, v10, 9
	v_readlane_b32 s34, v10, 10
	v_readlane_b32 s35, v10, 11
	v_readlane_b32 s36, v10, 12
	v_readlane_b32 s37, v10, 13
	v_readlane_b32 s38, v10, 14
	v_readlane_b32 s39, v10, 15
	v_lshlrev_b32_e32 v144, 16, v144
	v_lshlrev_b32_e32 v145, 16, v145
	v_lshlrev_b32_e32 v146, 16, v146
	v_lshlrev_b32_e32 v147, 16, v147
	v_lshlrev_b32_e32 v148, 16, v148
	v_lshlrev_b32_e32 v149, 16, v149
	v_lshlrev_b32_e32 v150, 16, v150
	v_lshlrev_b32_e32 v151, 16, v151
	v_mul_f32_e32 v144, s32, v144
	v_mul_f32_e32 v145, s33, v145
	v_mul_f32_e32 v146, s34, v146
	v_mul_f32_e32 v147, s35, v147
	v_mul_f32_e32 v148, s36, v148
	v_mul_f32_e32 v149, s37, v149
	v_mul_f32_e32 v150, s38, v150
	v_mul_f32_e32 v151, s39, v151
	v_cvt_pk_bf16_f32 v16, v144, v145
	v_cvt_pk_bf16_f32 v17, v146, v147
	v_cvt_pk_bf16_f32 v18, v148, v149
	v_cvt_pk_bf16_f32 v19, v150, v151
	global_store_dwordx4 v2, v[16:19], s[4:5] offset:256 nt
	s_waitcnt lgkmcnt(8)
	v_readlane_b32 s32, v10, 16
	v_readlane_b32 s33, v10, 17
	v_readlane_b32 s34, v10, 18
	v_readlane_b32 s35, v10, 19
	v_readlane_b32 s36, v10, 20
	v_readlane_b32 s37, v10, 21
	v_readlane_b32 s38, v10, 22
	v_readlane_b32 s39, v10, 23
	v_lshlrev_b32_e32 v184, 16, v184
	v_lshlrev_b32_e32 v185, 16, v185
	v_lshlrev_b32_e32 v186, 16, v186
	v_lshlrev_b32_e32 v187, 16, v187
	v_lshlrev_b32_e32 v188, 16, v188
	v_lshlrev_b32_e32 v189, 16, v189
	v_lshlrev_b32_e32 v190, 16, v190
	v_lshlrev_b32_e32 v191, 16, v191
	v_mul_f32_e32 v184, s32, v184
	v_mul_f32_e32 v185, s33, v185
	v_mul_f32_e32 v186, s34, v186
	v_mul_f32_e32 v187, s35, v187
	v_mul_f32_e32 v188, s36, v188
	v_mul_f32_e32 v189, s37, v189
	v_mul_f32_e32 v190, s38, v190
	v_mul_f32_e32 v191, s39, v191
	v_cvt_pk_bf16_f32 v12, v184, v185
	v_cvt_pk_bf16_f32 v13, v186, v187
	v_cvt_pk_bf16_f32 v14, v188, v189
	v_cvt_pk_bf16_f32 v15, v190, v191
	global_store_dwordx4 v2, v[12:15], s[4:5] offset:512 nt
	s_waitcnt lgkmcnt(0)
	v_readlane_b32 s32, v10, 24
	v_readlane_b32 s33, v10, 25
	v_readlane_b32 s34, v10, 26
	v_readlane_b32 s35, v10, 27
	v_readlane_b32 s36, v10, 28
	v_readlane_b32 s37, v10, 29
	v_readlane_b32 s38, v10, 30
	v_readlane_b32 s39, v10, 31
	v_lshlrev_b32_e32 v192, 16, v192
	v_lshlrev_b32_e32 v193, 16, v193
	v_lshlrev_b32_e32 v194, 16, v194
	v_lshlrev_b32_e32 v195, 16, v195
	v_lshlrev_b32_e32 v196, 16, v196
	v_lshlrev_b32_e32 v197, 16, v197
	v_lshlrev_b32_e32 v198, 16, v198
	v_lshlrev_b32_e32 v199, 16, v199
	v_mul_f32_e32 v192, s32, v192
	v_mul_f32_e32 v193, s33, v193
	v_mul_f32_e32 v194, s34, v194
	v_mul_f32_e32 v195, s35, v195
	v_mul_f32_e32 v196, s36, v196
	v_mul_f32_e32 v197, s37, v197
	v_mul_f32_e32 v198, s38, v198
	v_mul_f32_e32 v199, s39, v199
	v_cvt_pk_bf16_f32 v16, v192, v193
	v_cvt_pk_bf16_f32 v17, v194, v195
	v_cvt_pk_bf16_f32 v18, v196, v197
	v_cvt_pk_bf16_f32 v19, v198, v199
	global_store_dwordx4 v2, v[16:19], s[4:5] offset:768 nt
	s_branch .Lpd_done
